# P0 weight-transpose load loop fully unrolled: 32 loads in flight instead of 4 batches of 8 (on top of P3 epilogue change)
# speedup vs baseline: 1.0035x; 1.0035x over previous
; #define LAS __attribute__((address_space(3)))
; __device__ __forceinline__ unsigned pk2(float lo, float hi) { return pg8::cvt_pk_bf16(lo, hi); }
; __device__ __forceinline__ void transpose_item(const float* W, int K, int N, bf16_t* WT, int dst0, int src0, int mode, int nblk, LAS float* scr, int item, int lane) {
;     const int kb = item / nblk, nb = item % nblk, k0 = 64 * kb, n0 = 32 * nb;
;     const int sc = srccol(mode, n0 + (lane & 31), src0);
; #pragma unroll 8
;     for (int i = 0; i < 32; ++i) { const int kk = 2 * i + (lane >> 5); scr[kk * 33 + (lane & 31)] = __builtin_nontemporal_load(W + (size_t)(k0 + kk) * N + sc); }
;     asm volatile("s_waitcnt lgkmcnt(0)" ::: "memory");
;     const int c = lane & 7;
; #pragma unroll
;     for (int j = 0; j < 4; ++j) { const int n = (lane >> 3) + 8 * j; const LAS float* s = scr + (8 * c) * 33 + n;
;         u32x4 o; o.x = pk2(s[0 * 33], s[1 * 33]); o.y = pk2(s[2 * 33], s[3 * 33]); o.z = pk2(s[4 * 33], s[5 * 33]); o.w = pk2(s[6 * 33], s[7 * 33]);
;         *(u32x4*)(WT + (size_t)(dst0 + n0 + n) * K + k0 + 8 * c) = o; }
;     asm volatile("s_waitcnt lgkmcnt(0)" ::: "memory");
.LBB0_30:
	v_lshl_add_u64 v[34:35], v[16:17], 0, s[8:9]
	v_lshl_add_u64 v[36:37], v[14:15], 0, s[8:9]
	v_lshl_add_u64 v[38:39], v[12:13], 0, s[8:9]
	v_lshl_add_u64 v[40:41], v[10:11], 0, s[8:9]
	v_lshl_add_u64 v[42:43], v[8:9], 0, s[8:9]
	v_lshl_add_u64 v[44:45], v[6:7], 0, s[8:9]
	v_lshl_add_u64 v[46:47], v[4:5], 0, s[8:9]
	v_lshl_add_u64 v[48:49], v[2:3], 0, s[8:9]
	global_load_dword v104, v[34:35], off nt
	global_load_dword v105, v[36:37], off nt
	global_load_dword v106, v[38:39], off nt
	global_load_dword v107, v[40:41], off nt
	global_load_dword v108, v[42:43], off nt
	global_load_dword v109, v[44:45], off nt
	global_load_dword v110, v[46:47], off nt
	global_load_dword v111, v[48:49], off nt
	s_add_u32 s8, s8, 0xb0000
	s_addc_u32 s9, s9, 0
	v_lshl_add_u64 v[34:35], v[16:17], 0, s[8:9]
	v_lshl_add_u64 v[36:37], v[14:15], 0, s[8:9]
	v_lshl_add_u64 v[38:39], v[12:13], 0, s[8:9]
	v_lshl_add_u64 v[40:41], v[10:11], 0, s[8:9]
	v_lshl_add_u64 v[42:43], v[8:9], 0, s[8:9]
	v_lshl_add_u64 v[44:45], v[6:7], 0, s[8:9]
	v_lshl_add_u64 v[46:47], v[4:5], 0, s[8:9]
	v_lshl_add_u64 v[48:49], v[2:3], 0, s[8:9]
	global_load_dword v112, v[34:35], off nt
	global_load_dword v113, v[36:37], off nt
	global_load_dword v114, v[38:39], off nt
	global_load_dword v115, v[40:41], off nt
	global_load_dword v116, v[42:43], off nt
	global_load_dword v117, v[44:45], off nt
	global_load_dword v118, v[46:47], off nt
	global_load_dword v119, v[48:49], off nt
	s_add_u32 s8, s8, 0xb0000
	s_addc_u32 s9, s9, 0
	v_lshl_add_u64 v[34:35], v[16:17], 0, s[8:9]
	v_lshl_add_u64 v[36:37], v[14:15], 0, s[8:9]
	v_lshl_add_u64 v[38:39], v[12:13], 0, s[8:9]
	v_lshl_add_u64 v[40:41], v[10:11], 0, s[8:9]
	v_lshl_add_u64 v[42:43], v[8:9], 0, s[8:9]
	v_lshl_add_u64 v[44:45], v[6:7], 0, s[8:9]
	v_lshl_add_u64 v[46:47], v[4:5], 0, s[8:9]
	v_lshl_add_u64 v[48:49], v[2:3], 0, s[8:9]
	global_load_dword v120, v[34:35], off nt
	global_load_dword v121, v[36:37], off nt
	global_load_dword v122, v[38:39], off nt
	global_load_dword v123, v[40:41], off nt
	global_load_dword v124, v[42:43], off nt
	global_load_dword v125, v[44:45], off nt
	global_load_dword v126, v[46:47], off nt
	global_load_dword v127, v[48:49], off nt
	s_add_u32 s8, s8, 0xb0000
	s_addc_u32 s9, s9, 0
	v_lshl_add_u64 v[34:35], v[16:17], 0, s[8:9]
	v_lshl_add_u64 v[36:37], v[14:15], 0, s[8:9]
	v_lshl_add_u64 v[38:39], v[12:13], 0, s[8:9]
	v_lshl_add_u64 v[40:41], v[10:11], 0, s[8:9]
	v_lshl_add_u64 v[42:43], v[8:9], 0, s[8:9]
	v_lshl_add_u64 v[44:45], v[6:7], 0, s[8:9]
	v_lshl_add_u64 v[46:47], v[4:5], 0, s[8:9]
	v_lshl_add_u64 v[48:49], v[2:3], 0, s[8:9]
	global_load_dword v128, v[34:35], off nt
	global_load_dword v129, v[36:37], off nt
	global_load_dword v130, v[38:39], off nt
	global_load_dword v131, v[40:41], off nt
	global_load_dword v132, v[42:43], off nt
	global_load_dword v133, v[44:45], off nt
	global_load_dword v134, v[46:47], off nt
	global_load_dword v135, v[48:49], off nt
	s_add_u32 s8, s8, 0xb0000
	s_addc_u32 s9, s9, 0
	v_add_u32_e32 v34, 0x400, v32
	s_waitcnt vmcnt(30)
	ds_write2_b32 v32, v104, v105 offset1:66
	s_waitcnt vmcnt(28)
	ds_write2_b32 v32, v106, v107 offset0:132 offset1:198
	s_waitcnt vmcnt(26)
	ds_write2_b32 v34, v108, v109 offset0:8 offset1:74
	s_waitcnt vmcnt(24)
	ds_write2_b32 v34, v110, v111 offset0:140 offset1:206
	v_add_u32_e32 v32, 0x840, v32
	v_add_u32_e32 v34, 0x400, v32
	s_waitcnt vmcnt(22)
	ds_write2_b32 v32, v112, v113 offset1:66
	s_waitcnt vmcnt(20)
	ds_write2_b32 v32, v114, v115 offset0:132 offset1:198
	s_waitcnt vmcnt(18)
	ds_write2_b32 v34, v116, v117 offset0:8 offset1:74
	s_waitcnt vmcnt(16)
	ds_write2_b32 v34, v118, v119 offset0:140 offset1:206
	v_add_u32_e32 v32, 0x840, v32
	v_add_u32_e32 v34, 0x400, v32
	s_waitcnt vmcnt(14)
	ds_write2_b32 v32, v120, v121 offset1:66
	s_waitcnt vmcnt(12)
	ds_write2_b32 v32, v122, v123 offset0:132 offset1:198
	s_waitcnt vmcnt(10)
	ds_write2_b32 v34, v124, v125 offset0:8 offset1:74
	s_waitcnt vmcnt(8)
	ds_write2_b32 v34, v126, v127 offset0:140 offset1:206
	v_add_u32_e32 v32, 0x840, v32
	v_add_u32_e32 v34, 0x400, v32
	s_waitcnt vmcnt(6)
	ds_write2_b32 v32, v128, v129 offset1:66
	s_waitcnt vmcnt(4)
	ds_write2_b32 v32, v130, v131 offset0:132 offset1:198
	s_waitcnt vmcnt(2)
	ds_write2_b32 v34, v132, v133 offset0:8 offset1:74
	s_waitcnt vmcnt(0)
	ds_write2_b32 v34, v134, v135 offset0:140 offset1:206
	v_add_u32_e32 v32, 0x840, v32
	s_cmp_lg_u32 s8, 0x2c0000
	s_waitcnt lgkmcnt(0)
	ds_read2_b32 v[6:7], v20 offset0:33 offset1:41
	ds_read2_b32 v[8:9], v20 offset1:8
	ds_read2_b32 v[10:11], v20 offset0:66 offset1:74
	ds_read2_b32 v[12:13], v20 offset0:99 offset1:107
	ds_read2_b32 v[14:15], v20 offset0:132 offset1:140
	ds_read2_b32 v[16:17], v20 offset0:165 offset1:173
	ds_read2_b32 v[32:33], v20 offset0:198 offset1:206
	ds_read2_b32 v[34:35], v20 offset0:231 offset1:239
	v_or_b32_e32 v38, s12, v157
	s_ashr_i32 s5, s4, 31
	v_ashrrev_i32_e32 v39, 31, v38
	v_lshl_add_u64 v[36:37], s[4:5], 1, v[0:1]
	v_lshlrev_b64 v[38:39], 12, v[38:39]
	s_waitcnt lgkmcnt(6)
	v_cvt_pk_bf16_f32 v2, v8, v6
	s_waitcnt lgkmcnt(4)
	v_cvt_pk_bf16_f32 v3, v10, v12
	s_waitcnt lgkmcnt(2)
	v_cvt_pk_bf16_f32 v4, v14, v16
	s_waitcnt lgkmcnt(0)
	v_cvt_pk_bf16_f32 v5, v32, v34
	v_lshl_add_u64 v[38:39], v[36:37], 0, v[38:39]
	v_or_b32_e32 v6, s12, v21
	global_store_dwordx4 v[38:39], v[2:5], off
	s_add_i32 s11, s11, s34
	s_cmpk_gt_i32 s11, 0x2bff
	v_cvt_pk_bf16_f32 v2, v9, v7
	v_ashrrev_i32_e32 v7, 31, v6
	v_cvt_pk_bf16_f32 v3, v11, v13
	v_cvt_pk_bf16_f32 v4, v15, v17
	v_cvt_pk_bf16_f32 v5, v33, v35
	v_lshlrev_b64 v[6:7], 12, v[6:7]
	ds_read2_b32 v[8:9], v20 offset0:49 offset1:57
	ds_read2_b32 v[10:11], v20 offset0:16 offset1:24
	ds_read2_b32 v[12:13], v20 offset0:82 offset1:90
	ds_read2_b32 v[14:15], v20 offset0:115 offset1:123
	ds_read2_b32 v[16:17], v20 offset0:148 offset1:156
	ds_read2_b32 v[32:33], v20 offset0:181 offset1:189
	ds_read2_b32 v[34:35], v20 offset0:214 offset1:222
	ds_read2_b32 v[38:39], v20 offset0:247 offset1:255
	v_lshl_add_u64 v[6:7], v[36:37], 0, v[6:7]
	global_store_dwordx4 v[6:7], v[2:5], off
	v_or_b32_e32 v6, s12, v22
	v_ashrrev_i32_e32 v7, 31, v6
	v_lshlrev_b64 v[6:7], 12, v[6:7]
	s_waitcnt lgkmcnt(6)
	v_cvt_pk_bf16_f32 v2, v10, v8
	s_waitcnt lgkmcnt(4)
	v_cvt_pk_bf16_f32 v3, v12, v14
	s_waitcnt lgkmcnt(2)
	v_cvt_pk_bf16_f32 v4, v16, v32
	s_waitcnt lgkmcnt(0)
	v_cvt_pk_bf16_f32 v5, v34, v38
	v_lshl_add_u64 v[6:7], v[36:37], 0, v[6:7]
	global_store_dwordx4 v[6:7], v[2:5], off
	v_or_b32_e32 v6, s12, v23
	v_ashrrev_i32_e32 v7, 31, v6
	v_lshlrev_b64 v[6:7], 12, v[6:7]
	v_cvt_pk_bf16_f32 v2, v11, v9
	v_cvt_pk_bf16_f32 v3, v13, v15
	v_cvt_pk_bf16_f32 v4, v17, v33
	v_cvt_pk_bf16_f32 v5, v35, v39
	v_lshl_add_u64 v[6:7], v[36:37], 0, v[6:7]
	global_store_dwordx4 v[6:7], v[2:5], off
	s_waitcnt lgkmcnt(0)
	s_cbranch_scc0 .LBB0_29
